# v025 + G2 epilogue: f32 x1 stores marked non-temporal (they are not re-read until the last phase, keeps them from sitting dirty in L2 through G3)
# speedup vs baseline: 1.0106x; 1.0106x over previous
; __device__ __forceinline__ unsigned cvt_pk_bf16(float lo, float hi) { unsigned r; asm volatile("v_cvt_pk_bf16_f32 %0, %1, %2" : "=v"(r) : "v"(lo), "v"(hi)); return r; }
; __device__ __forceinline__ void st_wt8(void* ptr, u32x2 v) { asm volatile("global_store_dwordx2 %0, %1, off sc1" :: "v"(ptr), "v"(v) : "memory"); }
; __device__ __forceinline__ void st_wt4(void* ptr, unsigned v) { asm volatile("global_store_dword %0, %1, off sc1" :: "v"(ptr), "v"(v) : "memory"); }
;     __device__ __forceinline__ void operator()(const f32x4 (&acc)[2][2][4][2], const pg8::Unit& u, int wr, int wc, int fr, int fq) const {
;         const int row0 = u.pm * 256 + wr * 64 + fr, col0 = u.pn * 256 + wc * 32 + 4 * fq;
; #pragma unroll
;         for (int ai = 0; ai < 2; ++ai)
; #pragma unroll
;             for (int m = 0; m < 4; ++m) {
;                 const int row = row0 + ai * 128 + m * 16;
;                 float* orow = oy + (size_t)row * DM + col0;
;                 const float* xr = FIRST ? ((row < MP ? xp + (size_t)row * DM : xs + (size_t)(row - MP) * DM) + col0) : orow;
;                 float q = 0.f;
; #pragma unroll
;                 for (int bj = 0; bj < 2; ++bj)
; #pragma unroll
;                     for (int n = 0; n < 2; ++n) {
;                         const f32x4 xv = *(const f32x4*)(xr + bj * 128 + n * 16);
;                         const f32x4 o = xv + acc[ai][bj][m][n];
;                         *(f32x4*)(orow + bj * 128 + n * 16) = o;
;                         q += (o[0] * o[0] + o[1] * o[1]) + (o[2] * o[2] + o[3] * o[3]);
;                         if (FIRST) { u32x2 w; w.x = cvt_pk_bf16(o[0], o[1]); w.y = cvt_pk_bf16(o[2], o[3]); st_wt8(xb + (size_t)row * DM + col0 + bj * 128 + n * 16, w); }
;                     }
;                 q += __shfl_xor(q, 16); q += __shfl_xor(q, 32);
;                 if (fq == 0) { if (FIRST) st_wt4(ss + (size_t)row * 32 + u.pn * 4 + wc, __float_as_uint(q)); else ss[(size_t)row * 32 + u.pn * 4 + wc] = q; }
.LBB0_299:
	v_mbcnt_lo_u32_b32 v240, -1, 0
	v_mbcnt_hi_u32_b32 v240, -1, v240
	v_lshrrev_b32_e32 v240, 4, v240
	v_lshlrev_b32_e32 v240, 3, v240
	v_add_u32_e32 v240, 0xffffffe0, v240
	v_mov_b32_e32 v241, -1
	v_lshl_add_u32 v144, s63, 8, v148
	v_ashrrev_i32_e32 v145, 31, v144
	v_readlane_b32 s68, v234, 3
	v_add_u32_e32 v132, 0xffffe000, v144
	v_lshl_or_b32 v140, s10, 8, v150
	v_lshlrev_b64 v[156:157], 13, v[144:145]
	v_readlane_b32 s69, v234, 4
	v_readlane_b32 s70, v234, 5
	v_readlane_b32 s71, v234, 6
	v_lshlrev_b64 v[154:155], 13, v[132:133]
	v_ashrrev_i32_e32 v141, 31, v140
	v_lshl_add_u64 v[152:153], s[68:69], 0, v[156:157]
	v_lshl_add_u64 v[154:155], s[70:71], 0, v[154:155]
	v_cmp_gt_i32_e32 vcc, s54, v144
	v_lshlrev_b64 v[142:143], 2, v[140:141]
	v_lshlrev_b64 v[160:161], 12, v[144:145]
	v_cndmask_b32_e32 v153, v155, v153, vcc
	v_cndmask_b32_e32 v152, v154, v152, vcc
	v_lshl_add_u64 v[158:159], v[152:153], 0, v[142:143]
	v_mov_b32_e32 v232, v158
	v_mov_b32_e32 v233, v159
	global_load_dwordx4 v[164:167], v[232:233], off
	global_load_dwordx4 v[168:171], v[232:233], off offset:64
	global_load_dwordx4 v[172:175], v[232:233], off offset:512
	global_load_dwordx4 v[176:179], v[232:233], off offset:576
	s_mov_b64 s[98:99], 0x20000
	v_lshl_add_u64 v[192:193], v[232:233], 0, s[98:99]
	global_load_dwordx4 v[180:183], v[192:193], off
	global_load_dwordx4 v[184:187], v[192:193], off offset:64
	global_load_dwordx4 v[188:191], v[192:193], off offset:512
	global_load_dwordx4 v[196:199], v[192:193], off offset:576
	s_mov_b64 s[98:99], 0x40000
	v_lshl_add_u64 v[192:193], v[232:233], 0, s[98:99]
	global_load_dwordx4 v[200:203], v[192:193], off
	global_load_dwordx4 v[204:207], v[192:193], off offset:64
	global_load_dwordx4 v[208:211], v[192:193], off offset:512
	global_load_dwordx4 v[212:215], v[192:193], off offset:576
	s_mov_b64 s[98:99], 0x60000
	v_lshl_add_u64 v[192:193], v[232:233], 0, s[98:99]
	global_load_dwordx4 v[216:219], v[192:193], off
	global_load_dwordx4 v[220:223], v[192:193], off offset:64
	global_load_dwordx4 v[224:227], v[192:193], off offset:512
	global_load_dwordx4 v[228:231], v[192:193], off offset:576
	s_waitcnt vmcnt(0)
	v_mov_b32_e32 v152, v164
	v_mov_b32_e32 v153, v165
	v_mov_b32_e32 v154, v166
	v_mov_b32_e32 v155, v167
	v_lshl_add_u64 v[156:157], s[84:85], 0, v[156:157]
	v_lshl_add_u64 v[160:161], s[20:21], 0, v[160:161]
	v_lshl_add_u64 v[162:163], v[156:157], 0, v[142:143]
	v_lshl_add_u64 v[160:161], v[140:141], 1, v[160:161]
	v_lshl_add_u64 v[156:157], v[160:161], 0, 32
	s_lshl_b32 s42, s10, 2
	s_ashr_i32 s43, s42, 31
	v_readlane_b32 s72, v234, 7
	v_readlane_b32 s73, v234, 8
	v_readlane_b32 s74, v234, 9
	v_readlane_b32 s75, v234, 10
	v_readlane_b32 s76, v234, 11
	v_readlane_b32 s77, v234, 12
	v_readlane_b32 s78, v234, 13
	v_readlane_b32 s79, v234, 14
	v_readlane_b32 s80, v234, 15
	v_readlane_b32 s81, v234, 16
	v_readlane_b32 s82, v234, 17
	v_readlane_b32 s83, v234, 18
	v_pk_add_f32 v[126:127], v[126:127], v[154:155]
	v_pk_add_f32 v[124:125], v[124:125], v[152:153]
	global_store_dwordx4 v[162:163], v[124:127], off nt
	v_cvt_pk_bf16_f32 v236, v124, v125
	v_cvt_pk_bf16_f32 v237, v126, v127
	s_nop 0
	v_mov_b32_e32 v152, v168
	v_mov_b32_e32 v153, v169
	v_mov_b32_e32 v154, v170
	v_mov_b32_e32 v155, v171
	v_pk_add_f32 v[122:123], v[122:123], v[154:155]
	v_pk_add_f32 v[120:121], v[120:121], v[152:153]
	global_store_dwordx4 v[162:163], v[120:123], off offset:64 nt
	v_cvt_pk_bf16_f32 v238, v120, v121
	v_cvt_pk_bf16_f32 v239, v122, v123
	s_nop 0
	s_nop 1
	v_permlane32_swap_b32_e32 v236, v238
	v_permlane32_swap_b32_e32 v237, v239
	s_nop 1
	v_permlane16_swap_b32_e32 v236, v238
	v_permlane16_swap_b32_e32 v237, v239
	v_lshl_add_u64 v[242:243], v[156:157], 0, v[240:241]
	s_nop 0
	global_store_dwordx4 v[242:243], v[236:239], off sc1
	s_nop 1
	v_mov_b32_e32 v152, v172
	v_mov_b32_e32 v153, v173
	v_mov_b32_e32 v154, v174
	v_mov_b32_e32 v155, v175
	v_lshl_add_u64 v[156:157], v[160:161], 0, s[28:29]
	v_pk_add_f32 v[154:155], v[118:119], v[154:155]
	v_pk_add_f32 v[152:153], v[116:117], v[152:153]
	global_store_dwordx4 v[162:163], v[152:155], off offset:512 nt
	v_cvt_pk_bf16_f32 v236, v152, v153
	v_cvt_pk_bf16_f32 v237, v154, v155
	v_xor_b32_e32 v118, 32, v195
	v_mov_b32_e32 v156, v176
	v_mov_b32_e32 v157, v177
	v_mov_b32_e32 v158, v178
	v_mov_b32_e32 v159, v179
	v_and_b32_e32 v117, 64, v195
	v_xor_b32_e32 v116, 16, v195
	v_add_u32_e32 v117, 64, v117
	v_cmp_lt_i32_e32 vcc, v116, v117
	v_mul_f32_e32 v119, v127, v127
	v_fmac_f32_e32 v119, v126, v126
	v_cndmask_b32_e32 v116, v195, v116, vcc
	v_cmp_lt_i32_e32 vcc, v118, v117
	v_lshlrev_b32_e32 v116, 2, v116
	v_pk_add_f32 v[114:115], v[114:115], v[158:159]
	v_cndmask_b32_e32 v117, v195, v118, vcc
	v_mul_f32_e32 v118, v125, v125
	v_fmac_f32_e32 v118, v124, v124
	v_add_f32_e32 v118, v118, v119
	v_mul_f32_e32 v119, v121, v121
	v_mul_f32_e32 v121, v123, v123
	v_fmac_f32_e32 v119, v120, v120
	v_fmac_f32_e32 v121, v122, v122
	v_add_f32_e32 v119, v119, v121
	v_add_f32_e32 v118, v118, v119
	v_mul_f32_e32 v119, v153, v153
	v_mul_f32_e32 v120, v155, v155
	v_fmac_f32_e32 v119, v152, v152
	v_fmac_f32_e32 v120, v154, v154
	v_add_f32_e32 v119, v119, v120
	v_pk_add_f32 v[112:113], v[112:113], v[156:157]
	v_add_f32_e32 v118, v118, v119
	v_mul_f32_e32 v119, v113, v113
	v_mul_f32_e32 v120, v115, v115
	v_fmac_f32_e32 v119, v112, v112
	v_fmac_f32_e32 v120, v114, v114
	v_add_f32_e32 v119, v119, v120
	v_add_f32_e32 v122, v118, v119
	ds_bpermute_b32 v123, v116, v122
	global_store_dwordx4 v[162:163], v[112:115], off offset:576 nt
	v_cvt_pk_bf16_f32 v238, v112, v113
	v_cvt_pk_bf16_f32 v239, v114, v115
	v_lshl_add_u64 v[118:119], v[160:161], 0, s[30:31]
	s_nop 1
	v_permlane32_swap_b32_e32 v236, v238
	v_permlane32_swap_b32_e32 v237, v239
	s_nop 1
	v_permlane16_swap_b32_e32 v236, v238
	v_permlane16_swap_b32_e32 v237, v239
	v_lshl_add_u64 v[242:243], v[118:119], 0, v[240:241]
	s_nop 0
	global_store_dwordx4 v[242:243], v[236:239], off sc1
	s_nop 1
	s_waitcnt lgkmcnt(0)
	v_add_f32_e32 v112, v122, v123
	v_lshlrev_b32_e32 v114, 2, v117
	ds_bpermute_b32 v113, v114, v112
	s_and_saveexec_b64 s[44:45], s[4:5]
	s_cbranch_execz .LBB0_301
	s_waitcnt lgkmcnt(0)
	v_add_f32_e32 v115, v112, v113
	v_lshlrev_b64 v[112:113], 7, v[144:145]
	v_lshl_add_u64 v[112:113], s[2:3], 0, v[112:113]
	v_lshl_add_u64 v[112:113], s[42:43], 2, v[112:113]
	s_lshl_b32 s10, s55, 2
	v_lshl_add_u64 v[112:113], v[112:113], 0, s[10:11]
	global_store_dword v[112:113], v115, off sc1
; __device__ __forceinline__ unsigned cvt_pk_bf16(float lo, float hi) { unsigned r; asm volatile("v_cvt_pk_bf16_f32 %0, %1, %2" : "=v"(r) : "v"(lo), "v"(hi)); return r; }
; __device__ __forceinline__ void st_wt8(void* ptr, u32x2 v) { asm volatile("global_store_dwordx2 %0, %1, off sc1" :: "v"(ptr), "v"(v) : "memory"); }
; __device__ __forceinline__ void st_wt4(void* ptr, unsigned v) { asm volatile("global_store_dword %0, %1, off sc1" :: "v"(ptr), "v"(v) : "memory"); }
;     __device__ __forceinline__ void operator()(const f32x4 (&acc)[2][2][4][2], const pg8::Unit& u, int wr, int wc, int fr, int fq) const {
;     ...
;                 const int row = row0 + ai * 128 + m * 16;
;                 float* orow = oy + (size_t)row * DM + col0;
;                 const float* xr = FIRST ? ((row < MP ? xp + (size_t)row * DM : xs + (size_t)(row - MP) * DM) + col0) : orow;
;                 float q = 0.f;
; #pragma unroll
;                 for (int bj = 0; bj < 2; ++bj)
; #pragma unroll
;                     for (int n = 0; n < 2; ++n) {
;                         const f32x4 xv = *(const f32x4*)(xr + bj * 128 + n * 16);
;                         const f32x4 o = xv + acc[ai][bj][m][n];
;                         *(f32x4*)(orow + bj * 128 + n * 16) = o;
;                         q += (o[0] * o[0] + o[1] * o[1]) + (o[2] * o[2] + o[3] * o[3]);
;                         if (FIRST) { u32x2 w; w.x = cvt_pk_bf16(o[0], o[1]); w.y = cvt_pk_bf16(o[2], o[3]); st_wt8(xb + (size_t)row * DM + col0 + bj * 128 + n * 16, w); }
;                     }
;                 q += __shfl_xor(q, 16); q += __shfl_xor(q, 32);
;                 if (fq == 0) { if (FIRST) st_wt4(ss + (size_t)row * 32 + u.pn * 4 + wc, __float_as_uint(q)); else ss[(size_t)row * 32 + u.pn * 4 + wc] = q; }
.LBB0_301:
	s_or_b64 exec, exec, s[44:45]
	v_or_b32_e32 v112, 16, v144
	s_waitcnt lgkmcnt(0)
	v_ashrrev_i32_e32 v113, 31, v112
	v_readlane_b32 s68, v234, 3
	v_add_u32_e32 v132, 0xffffe010, v144
	v_lshlrev_b64 v[122:123], 13, v[112:113]
	v_readlane_b32 s69, v234, 4
	v_readlane_b32 s70, v234, 5
	v_readlane_b32 s71, v234, 6
	v_lshlrev_b64 v[120:121], 13, v[132:133]
	v_lshl_add_u64 v[118:119], s[68:69], 0, v[122:123]
	v_lshl_add_u64 v[120:121], s[70:71], 0, v[120:121]
	v_cmp_gt_i32_e32 vcc, s54, v112
	v_lshlrev_b64 v[126:127], 12, v[112:113]
	v_lshl_add_u64 v[122:123], s[84:85], 0, v[122:123]
	v_cndmask_b32_e32 v119, v121, v119, vcc
	v_cndmask_b32_e32 v118, v120, v118, vcc
	v_lshl_add_u64 v[124:125], v[118:119], 0, v[142:143]
	v_mov_b32_e32 v118, v180
	v_mov_b32_e32 v119, v181
	v_mov_b32_e32 v120, v182
	v_mov_b32_e32 v121, v183
	v_lshl_add_u64 v[126:127], s[20:21], 0, v[126:127]
	v_lshl_add_u64 v[122:123], v[122:123], 0, v[142:143]
	v_lshl_add_u64 v[126:127], v[140:141], 1, v[126:127]
	v_lshl_add_u64 v[152:153], v[126:127], 0, 32
	v_readlane_b32 s72, v234, 7
	v_readlane_b32 s73, v234, 8
	v_readlane_b32 s74, v234, 9
	v_readlane_b32 s75, v234, 10
	v_readlane_b32 s76, v234, 11
	v_readlane_b32 s77, v234, 12
	v_readlane_b32 s78, v234, 13
	v_readlane_b32 s79, v234, 14
	v_readlane_b32 s80, v234, 15
	v_readlane_b32 s81, v234, 16
	v_readlane_b32 s82, v234, 17
	v_readlane_b32 s83, v234, 18
	v_pk_add_f32 v[110:111], v[110:111], v[120:121]
	v_pk_add_f32 v[108:109], v[108:109], v[118:119]
	global_store_dwordx4 v[122:123], v[108:111], off nt
	v_cvt_pk_bf16_f32 v236, v108, v109
	v_cvt_pk_bf16_f32 v237, v110, v111
	s_nop 0
	v_mov_b32_e32 v118, v184
	v_mov_b32_e32 v119, v185
	v_mov_b32_e32 v120, v186
	v_mov_b32_e32 v121, v187
	v_mul_f32_e32 v109, v109, v109
	v_mul_f32_e32 v111, v111, v111
	v_fmac_f32_e32 v109, v108, v108
	v_fmac_f32_e32 v111, v110, v110
	v_add_f32_e32 v108, v109, v111
	v_pk_add_f32 v[106:107], v[106:107], v[120:121]
	v_pk_add_f32 v[104:105], v[104:105], v[118:119]
	global_store_dwordx4 v[122:123], v[104:107], off offset:64 nt
	v_cvt_pk_bf16_f32 v238, v104, v105
	v_cvt_pk_bf16_f32 v239, v106, v107
	s_nop 0
	s_nop 1
	v_permlane32_swap_b32_e32 v236, v238
	v_permlane32_swap_b32_e32 v237, v239
	s_nop 1
	v_permlane16_swap_b32_e32 v236, v238
	v_permlane16_swap_b32_e32 v237, v239
	v_lshl_add_u64 v[242:243], v[152:153], 0, v[240:241]
	s_nop 0
	global_store_dwordx4 v[242:243], v[236:239], off sc1
	s_nop 1
	v_mov_b32_e32 v118, v188
	v_mov_b32_e32 v119, v189
	v_mov_b32_e32 v120, v190
	v_mov_b32_e32 v121, v191
	v_lshl_add_u64 v[152:153], v[126:127], 0, s[28:29]
	v_mul_f32_e32 v105, v105, v105
	v_mul_f32_e32 v107, v107, v107
	v_fmac_f32_e32 v105, v104, v104
	v_fmac_f32_e32 v107, v106, v106
	v_add_f32_e32 v104, v105, v107
	v_add_f32_e32 v104, v108, v104
	v_pk_add_f32 v[102:103], v[102:103], v[120:121]
	v_pk_add_f32 v[100:101], v[100:101], v[118:119]
	global_store_dwordx4 v[122:123], v[100:103], off offset:512 nt
	v_cvt_pk_bf16_f32 v236, v100, v101
	v_cvt_pk_bf16_f32 v237, v102, v103
	s_nop 0
	v_mov_b32_e32 v118, v196
	v_mov_b32_e32 v119, v197
	v_mov_b32_e32 v120, v198
	v_mov_b32_e32 v121, v199
	v_mul_f32_e32 v101, v101, v101
	v_mul_f32_e32 v103, v103, v103
	v_fmac_f32_e32 v101, v100, v100
	v_fmac_f32_e32 v103, v102, v102
	v_add_f32_e32 v100, v101, v103
	v_add_f32_e32 v100, v104, v100
	v_pk_add_f32 v[98:99], v[98:99], v[120:121]
	v_pk_add_f32 v[96:97], v[96:97], v[118:119]
	v_mul_f32_e32 v102, v99, v99
	v_mul_f32_e32 v101, v97, v97
	v_fmac_f32_e32 v101, v96, v96
	v_fmac_f32_e32 v102, v98, v98
	v_add_f32_e32 v101, v101, v102
	v_add_f32_e32 v102, v100, v101
	ds_bpermute_b32 v103, v116, v102
	global_store_dwordx4 v[122:123], v[96:99], off offset:576 nt
	v_cvt_pk_bf16_f32 v238, v96, v97
	v_cvt_pk_bf16_f32 v239, v98, v99
	s_waitcnt lgkmcnt(0)
	s_nop 0
	v_add_f32_e32 v96, v102, v103
	ds_bpermute_b32 v97, v114, v96
	v_lshl_add_u64 v[98:99], v[126:127], 0, s[30:31]
	s_nop 1
	v_permlane32_swap_b32_e32 v236, v238
	v_permlane32_swap_b32_e32 v237, v239
	s_nop 1
	v_permlane16_swap_b32_e32 v236, v238
	v_permlane16_swap_b32_e32 v237, v239
	v_lshl_add_u64 v[242:243], v[98:99], 0, v[240:241]
	s_nop 0
	global_store_dwordx4 v[242:243], v[236:239], off sc1
	s_nop 1
	s_and_saveexec_b64 s[44:45], s[4:5]
	s_cbranch_execz .LBB0_303
	s_waitcnt lgkmcnt(0)
	v_add_f32_e32 v98, v96, v97
	v_lshlrev_b64 v[96:97], 7, v[112:113]
	v_lshl_add_u64 v[96:97], s[2:3], 0, v[96:97]
	v_lshl_add_u64 v[96:97], s[42:43], 2, v[96:97]
	s_lshl_b32 s10, s55, 2
	v_lshl_add_u64 v[96:97], v[96:97], 0, s[10:11]
	global_store_dword v[96:97], v98, off sc1
; __device__ __forceinline__ unsigned cvt_pk_bf16(float lo, float hi) { unsigned r; asm volatile("v_cvt_pk_bf16_f32 %0, %1, %2" : "=v"(r) : "v"(lo), "v"(hi)); return r; }
; __device__ __forceinline__ void st_wt8(void* ptr, u32x2 v) { asm volatile("global_store_dwordx2 %0, %1, off sc1" :: "v"(ptr), "v"(v) : "memory"); }
; __device__ __forceinline__ void st_wt4(void* ptr, unsigned v) { asm volatile("global_store_dword %0, %1, off sc1" :: "v"(ptr), "v"(v) : "memory"); }
;     __device__ __forceinline__ void operator()(const f32x4 (&acc)[2][2][4][2], const pg8::Unit& u, int wr, int wc, int fr, int fq) const {
;     ...
;                 const int row = row0 + ai * 128 + m * 16;
;                 float* orow = oy + (size_t)row * DM + col0;
;                 const float* xr = FIRST ? ((row < MP ? xp + (size_t)row * DM : xs + (size_t)(row - MP) * DM) + col0) : orow;
;                 float q = 0.f;
; #pragma unroll
;                 for (int bj = 0; bj < 2; ++bj)
; #pragma unroll
;                     for (int n = 0; n < 2; ++n) {
;                         const f32x4 xv = *(const f32x4*)(xr + bj * 128 + n * 16);
;                         const f32x4 o = xv + acc[ai][bj][m][n];
;                         *(f32x4*)(orow + bj * 128 + n * 16) = o;
;                         q += (o[0] * o[0] + o[1] * o[1]) + (o[2] * o[2] + o[3] * o[3]);
;                         if (FIRST) { u32x2 w; w.x = cvt_pk_bf16(o[0], o[1]); w.y = cvt_pk_bf16(o[2], o[3]); st_wt8(xb + (size_t)row * DM + col0 + bj * 128 + n * 16, w); }
;                     }
;                 q += __shfl_xor(q, 16); q += __shfl_xor(q, 32);
;                 if (fq == 0) { if (FIRST) st_wt4(ss + (size_t)row * 32 + u.pn * 4 + wc, __float_as_uint(q)); else ss[(size_t)row * 32 + u.pn * 4 + wc] = q; }
.LBB0_303:
	s_or_b64 exec, exec, s[44:45]
	v_or_b32_e32 v96, 32, v144
	s_waitcnt lgkmcnt(0)
	v_ashrrev_i32_e32 v97, 31, v96
	v_readlane_b32 s68, v234, 3
	v_add_u32_e32 v132, 0xffffe020, v144
	v_lshlrev_b64 v[102:103], 13, v[96:97]
	v_readlane_b32 s69, v234, 4
	v_readlane_b32 s70, v234, 5
	v_readlane_b32 s71, v234, 6
	v_lshlrev_b64 v[100:101], 13, v[132:133]
	v_lshl_add_u64 v[98:99], s[68:69], 0, v[102:103]
	v_lshl_add_u64 v[100:101], s[70:71], 0, v[100:101]
	v_cmp_gt_i32_e32 vcc, s54, v96
	v_lshlrev_b64 v[106:107], 12, v[96:97]
	v_lshl_add_u64 v[102:103], s[84:85], 0, v[102:103]
	v_cndmask_b32_e32 v99, v101, v99, vcc
	v_cndmask_b32_e32 v98, v100, v98, vcc
	v_lshl_add_u64 v[104:105], v[98:99], 0, v[142:143]
	v_mov_b32_e32 v98, v200
	v_mov_b32_e32 v99, v201
	v_mov_b32_e32 v100, v202
	v_mov_b32_e32 v101, v203
	v_lshl_add_u64 v[106:107], s[20:21], 0, v[106:107]
	v_lshl_add_u64 v[102:103], v[102:103], 0, v[142:143]
	v_lshl_add_u64 v[106:107], v[140:141], 1, v[106:107]
	v_lshl_add_u64 v[108:109], v[106:107], 0, 32
	v_readlane_b32 s72, v234, 7
	v_readlane_b32 s73, v234, 8
	v_readlane_b32 s74, v234, 9
	v_readlane_b32 s75, v234, 10
	v_readlane_b32 s76, v234, 11
	v_readlane_b32 s77, v234, 12
	v_readlane_b32 s78, v234, 13
	v_readlane_b32 s79, v234, 14
	v_readlane_b32 s80, v234, 15
	v_readlane_b32 s81, v234, 16
	v_readlane_b32 s82, v234, 17
	v_readlane_b32 s83, v234, 18
	v_pk_add_f32 v[94:95], v[94:95], v[100:101]
	v_pk_add_f32 v[92:93], v[92:93], v[98:99]
	global_store_dwordx4 v[102:103], v[92:95], off nt
	v_cvt_pk_bf16_f32 v236, v92, v93
	v_cvt_pk_bf16_f32 v237, v94, v95
	s_nop 0
	v_mov_b32_e32 v98, v204
	v_mov_b32_e32 v99, v205
	v_mov_b32_e32 v100, v206
	v_mov_b32_e32 v101, v207
	v_mul_f32_e32 v93, v93, v93
	v_mul_f32_e32 v95, v95, v95
	v_fmac_f32_e32 v93, v92, v92
	v_fmac_f32_e32 v95, v94, v94
	v_add_f32_e32 v92, v93, v95
	v_pk_add_f32 v[90:91], v[90:91], v[100:101]
	v_pk_add_f32 v[88:89], v[88:89], v[98:99]
	global_store_dwordx4 v[102:103], v[88:91], off offset:64 nt
	v_cvt_pk_bf16_f32 v238, v88, v89
	v_cvt_pk_bf16_f32 v239, v90, v91
	s_nop 0
	s_nop 1
	v_permlane32_swap_b32_e32 v236, v238
	v_permlane32_swap_b32_e32 v237, v239
	s_nop 1
	v_permlane16_swap_b32_e32 v236, v238
	v_permlane16_swap_b32_e32 v237, v239
	v_lshl_add_u64 v[242:243], v[108:109], 0, v[240:241]
	s_nop 0
	global_store_dwordx4 v[242:243], v[236:239], off sc1
	s_nop 1
	v_mov_b32_e32 v98, v208
	v_mov_b32_e32 v99, v209
	v_mov_b32_e32 v100, v210
	v_mov_b32_e32 v101, v211
	v_lshl_add_u64 v[108:109], v[106:107], 0, s[28:29]
	v_mul_f32_e32 v89, v89, v89
	v_mul_f32_e32 v91, v91, v91
	v_fmac_f32_e32 v89, v88, v88
	v_fmac_f32_e32 v91, v90, v90
	v_add_f32_e32 v88, v89, v91
	v_add_f32_e32 v88, v92, v88
	v_pk_add_f32 v[86:87], v[86:87], v[100:101]
	v_pk_add_f32 v[84:85], v[84:85], v[98:99]
	global_store_dwordx4 v[102:103], v[84:87], off offset:512 nt
	v_cvt_pk_bf16_f32 v236, v84, v85
	v_cvt_pk_bf16_f32 v237, v86, v87
	s_nop 0
	v_mov_b32_e32 v98, v212
	v_mov_b32_e32 v99, v213
	v_mov_b32_e32 v100, v214
	v_mov_b32_e32 v101, v215
	v_mul_f32_e32 v85, v85, v85
	v_mul_f32_e32 v87, v87, v87
	v_fmac_f32_e32 v85, v84, v84
	v_fmac_f32_e32 v87, v86, v86
	v_add_f32_e32 v84, v85, v87
	v_add_f32_e32 v84, v88, v84
	v_pk_add_f32 v[82:83], v[82:83], v[100:101]
	v_pk_add_f32 v[80:81], v[80:81], v[98:99]
	v_mul_f32_e32 v86, v83, v83
	v_mul_f32_e32 v85, v81, v81
	v_fmac_f32_e32 v85, v80, v80
	v_fmac_f32_e32 v86, v82, v82
	v_add_f32_e32 v85, v85, v86
	v_add_f32_e32 v86, v84, v85
	ds_bpermute_b32 v87, v116, v86
	global_store_dwordx4 v[102:103], v[80:83], off offset:576 nt
	v_cvt_pk_bf16_f32 v238, v80, v81
	v_cvt_pk_bf16_f32 v239, v82, v83
	s_waitcnt lgkmcnt(0)
	s_nop 0
	v_add_f32_e32 v80, v86, v87
	ds_bpermute_b32 v81, v114, v80
	v_lshl_add_u64 v[82:83], v[106:107], 0, s[30:31]
	s_nop 1
	v_permlane32_swap_b32_e32 v236, v238
	v_permlane32_swap_b32_e32 v237, v239
	s_nop 1
	v_permlane16_swap_b32_e32 v236, v238
	v_permlane16_swap_b32_e32 v237, v239
	v_lshl_add_u64 v[242:243], v[82:83], 0, v[240:241]
	s_nop 0
	global_store_dwordx4 v[242:243], v[236:239], off sc1
	s_nop 1
	s_and_saveexec_b64 s[44:45], s[4:5]
	s_cbranch_execz .LBB0_305
	s_waitcnt lgkmcnt(0)
	v_add_f32_e32 v82, v80, v81
	v_lshlrev_b64 v[80:81], 7, v[96:97]
	v_lshl_add_u64 v[80:81], s[2:3], 0, v[80:81]
	v_lshl_add_u64 v[80:81], s[42:43], 2, v[80:81]
	s_lshl_b32 s10, s55, 2
	v_lshl_add_u64 v[80:81], v[80:81], 0, s[10:11]
	global_store_dword v[80:81], v82, off sc1
; __device__ __forceinline__ unsigned cvt_pk_bf16(float lo, float hi) { unsigned r; asm volatile("v_cvt_pk_bf16_f32 %0, %1, %2" : "=v"(r) : "v"(lo), "v"(hi)); return r; }
; __device__ __forceinline__ void st_wt8(void* ptr, u32x2 v) { asm volatile("global_store_dwordx2 %0, %1, off sc1" :: "v"(ptr), "v"(v) : "memory"); }
; __device__ __forceinline__ void st_wt4(void* ptr, unsigned v) { asm volatile("global_store_dword %0, %1, off sc1" :: "v"(ptr), "v"(v) : "memory"); }
;     __device__ __forceinline__ void operator()(const f32x4 (&acc)[2][2][4][2], const pg8::Unit& u, int wr, int wc, int fr, int fq) const {
;     ...
;                 const int row = row0 + ai * 128 + m * 16;
;                 float* orow = oy + (size_t)row * DM + col0;
;                 const float* xr = FIRST ? ((row < MP ? xp + (size_t)row * DM : xs + (size_t)(row - MP) * DM) + col0) : orow;
;                 float q = 0.f;
; #pragma unroll
;                 for (int bj = 0; bj < 2; ++bj)
; #pragma unroll
;                     for (int n = 0; n < 2; ++n) {
;                         const f32x4 xv = *(const f32x4*)(xr + bj * 128 + n * 16);
;                         const f32x4 o = xv + acc[ai][bj][m][n];
;                         *(f32x4*)(orow + bj * 128 + n * 16) = o;
;                         q += (o[0] * o[0] + o[1] * o[1]) + (o[2] * o[2] + o[3] * o[3]);
;                         if (FIRST) { u32x2 w; w.x = cvt_pk_bf16(o[0], o[1]); w.y = cvt_pk_bf16(o[2], o[3]); st_wt8(xb + (size_t)row * DM + col0 + bj * 128 + n * 16, w); }
;                     }
;                 q += __shfl_xor(q, 16); q += __shfl_xor(q, 32);
;                 if (fq == 0) { if (FIRST) st_wt4(ss + (size_t)row * 32 + u.pn * 4 + wc, __float_as_uint(q)); else ss[(size_t)row * 32 + u.pn * 4 + wc] = q; }
.LBB0_305:
	s_or_b64 exec, exec, s[44:45]
	v_or_b32_e32 v80, 48, v144
	s_waitcnt lgkmcnt(0)
	v_ashrrev_i32_e32 v81, 31, v80
	v_readlane_b32 s68, v234, 3
	v_add_u32_e32 v132, 0xffffe030, v144
	v_lshlrev_b64 v[86:87], 13, v[80:81]
	v_readlane_b32 s69, v234, 4
	v_readlane_b32 s70, v234, 5
	v_readlane_b32 s71, v234, 6
	v_lshlrev_b64 v[84:85], 13, v[132:133]
	v_lshl_add_u64 v[82:83], s[68:69], 0, v[86:87]
	v_lshl_add_u64 v[84:85], s[70:71], 0, v[84:85]
	v_cmp_gt_i32_e32 vcc, s54, v80
	v_lshlrev_b64 v[90:91], 12, v[80:81]
	v_lshl_add_u64 v[86:87], s[84:85], 0, v[86:87]
	v_cndmask_b32_e32 v83, v85, v83, vcc
	v_cndmask_b32_e32 v82, v84, v82, vcc
	v_lshl_add_u64 v[88:89], v[82:83], 0, v[142:143]
	v_mov_b32_e32 v82, v216
	v_mov_b32_e32 v83, v217
	v_mov_b32_e32 v84, v218
	v_mov_b32_e32 v85, v219
	v_lshl_add_u64 v[90:91], s[20:21], 0, v[90:91]
	v_lshl_add_u64 v[86:87], v[86:87], 0, v[142:143]
	v_lshl_add_u64 v[90:91], v[140:141], 1, v[90:91]
	v_lshl_add_u64 v[92:93], v[90:91], 0, 32
	v_readlane_b32 s72, v234, 7
	v_readlane_b32 s73, v234, 8
	v_readlane_b32 s74, v234, 9
	v_readlane_b32 s75, v234, 10
	v_readlane_b32 s76, v234, 11
	v_readlane_b32 s77, v234, 12
	v_readlane_b32 s78, v234, 13
	v_readlane_b32 s79, v234, 14
	v_readlane_b32 s80, v234, 15
	v_readlane_b32 s81, v234, 16
	v_readlane_b32 s82, v234, 17
	v_readlane_b32 s83, v234, 18
	v_pk_add_f32 v[78:79], v[78:79], v[84:85]
	v_pk_add_f32 v[76:77], v[76:77], v[82:83]
	global_store_dwordx4 v[86:87], v[76:79], off nt
	v_cvt_pk_bf16_f32 v236, v76, v77
	v_cvt_pk_bf16_f32 v237, v78, v79
	s_nop 0
	v_mov_b32_e32 v82, v220
	v_mov_b32_e32 v83, v221
	v_mov_b32_e32 v84, v222
	v_mov_b32_e32 v85, v223
	v_mul_f32_e32 v77, v77, v77
	v_mul_f32_e32 v79, v79, v79
	v_fmac_f32_e32 v77, v76, v76
	v_fmac_f32_e32 v79, v78, v78
	v_add_f32_e32 v76, v77, v79
	v_pk_add_f32 v[74:75], v[74:75], v[84:85]
	v_pk_add_f32 v[72:73], v[72:73], v[82:83]
	global_store_dwordx4 v[86:87], v[72:75], off offset:64 nt
	v_cvt_pk_bf16_f32 v238, v72, v73
	v_cvt_pk_bf16_f32 v239, v74, v75
	s_nop 0
	s_nop 1
	v_permlane32_swap_b32_e32 v236, v238
	v_permlane32_swap_b32_e32 v237, v239
	s_nop 1
	v_permlane16_swap_b32_e32 v236, v238
	v_permlane16_swap_b32_e32 v237, v239
	v_lshl_add_u64 v[242:243], v[92:93], 0, v[240:241]
	s_nop 0
	global_store_dwordx4 v[242:243], v[236:239], off sc1
	s_nop 1
	v_mov_b32_e32 v82, v224
	v_mov_b32_e32 v83, v225
	v_mov_b32_e32 v84, v226
	v_mov_b32_e32 v85, v227
	v_lshl_add_u64 v[92:93], v[90:91], 0, s[28:29]
	v_mul_f32_e32 v73, v73, v73
	v_mul_f32_e32 v75, v75, v75
	v_fmac_f32_e32 v73, v72, v72
	v_fmac_f32_e32 v75, v74, v74
	v_add_f32_e32 v72, v73, v75
	v_add_f32_e32 v72, v76, v72
	v_pk_add_f32 v[70:71], v[70:71], v[84:85]
	v_pk_add_f32 v[68:69], v[68:69], v[82:83]
	global_store_dwordx4 v[86:87], v[68:71], off offset:512 nt
	v_cvt_pk_bf16_f32 v236, v68, v69
	v_cvt_pk_bf16_f32 v237, v70, v71
	s_nop 0
	v_mov_b32_e32 v82, v228
	v_mov_b32_e32 v83, v229
	v_mov_b32_e32 v84, v230
	v_mov_b32_e32 v85, v231
	v_mul_f32_e32 v69, v69, v69
	v_mul_f32_e32 v71, v71, v71
	v_fmac_f32_e32 v69, v68, v68
	v_fmac_f32_e32 v71, v70, v70
	v_add_f32_e32 v68, v69, v71
	v_add_f32_e32 v68, v72, v68
	v_pk_add_f32 v[66:67], v[66:67], v[84:85]
	v_pk_add_f32 v[64:65], v[64:65], v[82:83]
	v_mul_f32_e32 v70, v67, v67
	v_mul_f32_e32 v69, v65, v65
	v_fmac_f32_e32 v69, v64, v64
	v_fmac_f32_e32 v70, v66, v66
	v_add_f32_e32 v69, v69, v70
	v_add_f32_e32 v70, v68, v69
	ds_bpermute_b32 v71, v116, v70
	global_store_dwordx4 v[86:87], v[64:67], off offset:576 nt
	v_cvt_pk_bf16_f32 v238, v64, v65
	v_cvt_pk_bf16_f32 v239, v66, v67
	s_waitcnt lgkmcnt(0)
	s_nop 0
	v_add_f32_e32 v64, v70, v71
	ds_bpermute_b32 v65, v114, v64
	v_lshl_add_u64 v[66:67], v[90:91], 0, s[30:31]
	s_nop 1
	v_permlane32_swap_b32_e32 v236, v238
	v_permlane32_swap_b32_e32 v237, v239
	s_nop 1
	v_permlane16_swap_b32_e32 v236, v238
	v_permlane16_swap_b32_e32 v237, v239
	v_lshl_add_u64 v[242:243], v[66:67], 0, v[240:241]
	s_nop 0
	global_store_dwordx4 v[242:243], v[236:239], off sc1
	s_nop 1
	s_and_saveexec_b64 s[44:45], s[4:5]
	s_cbranch_execz .LBB0_307
	s_waitcnt lgkmcnt(0)
	v_add_f32_e32 v66, v64, v65
	v_lshlrev_b64 v[64:65], 7, v[80:81]
	v_lshl_add_u64 v[64:65], s[2:3], 0, v[64:65]
	v_lshl_add_u64 v[64:65], s[42:43], 2, v[64:65]
	s_lshl_b32 s10, s55, 2
	v_lshl_add_u64 v[64:65], v[64:65], 0, s[10:11]
	global_store_dword v[64:65], v66, off sc1
; __device__ __forceinline__ unsigned cvt_pk_bf16(float lo, float hi) { unsigned r; asm volatile("v_cvt_pk_bf16_f32 %0, %1, %2" : "=v"(r) : "v"(lo), "v"(hi)); return r; }
; __device__ __forceinline__ void st_wt8(void* ptr, u32x2 v) { asm volatile("global_store_dwordx2 %0, %1, off sc1" :: "v"(ptr), "v"(v) : "memory"); }
; __device__ __forceinline__ void st_wt4(void* ptr, unsigned v) { asm volatile("global_store_dword %0, %1, off sc1" :: "v"(ptr), "v"(v) : "memory"); }
;     __device__ __forceinline__ void operator()(const f32x4 (&acc)[2][2][4][2], const pg8::Unit& u, int wr, int wc, int fr, int fq) const {
;     ...
;                 const int row = row0 + ai * 128 + m * 16;
;                 float* orow = oy + (size_t)row * DM + col0;
;                 const float* xr = FIRST ? ((row < MP ? xp + (size_t)row * DM : xs + (size_t)(row - MP) * DM) + col0) : orow;
;                 float q = 0.f;
; #pragma unroll
;                 for (int bj = 0; bj < 2; ++bj)
; #pragma unroll
;                     for (int n = 0; n < 2; ++n) {
;                         const f32x4 xv = *(const f32x4*)(xr + bj * 128 + n * 16);
;                         const f32x4 o = xv + acc[ai][bj][m][n];
;                         *(f32x4*)(orow + bj * 128 + n * 16) = o;
;                         q += (o[0] * o[0] + o[1] * o[1]) + (o[2] * o[2] + o[3] * o[3]);
;                         if (FIRST) { u32x2 w; w.x = cvt_pk_bf16(o[0], o[1]); w.y = cvt_pk_bf16(o[2], o[3]); st_wt8(xb + (size_t)row * DM + col0 + bj * 128 + n * 16, w); }
;                     }
;                 q += __shfl_xor(q, 16); q += __shfl_xor(q, 32);
;                 if (fq == 0) { if (FIRST) st_wt4(ss + (size_t)row * 32 + u.pn * 4 + wc, __float_as_uint(q)); else ss[(size_t)row * 32 + u.pn * 4 + wc] = q; }
.LBB0_307:
	s_or_b64 exec, exec, s[44:45]
	v_add_u32_e32 v64, 0x80, v144
	s_waitcnt lgkmcnt(0)
	v_ashrrev_i32_e32 v65, 31, v64
	v_readlane_b32 s68, v234, 3
	v_add_u32_e32 v132, 0xffffe080, v144
	v_lshlrev_b64 v[70:71], 13, v[64:65]
	v_readlane_b32 s69, v234, 4
	v_readlane_b32 s70, v234, 5
	v_readlane_b32 s71, v234, 6
	v_lshlrev_b64 v[68:69], 13, v[132:133]
	s_movk_i32 s9, 0x1f80
	v_lshl_add_u64 v[66:67], s[68:69], 0, v[70:71]
	v_lshl_add_u64 v[68:69], s[70:71], 0, v[68:69]
	v_cmp_gt_i32_e32 vcc, s9, v144
	v_lshlrev_b64 v[74:75], 12, v[64:65]
	v_lshl_add_u64 v[70:71], s[84:85], 0, v[70:71]
	v_cndmask_b32_e32 v67, v69, v67, vcc
	v_cndmask_b32_e32 v66, v68, v66, vcc
	v_lshl_add_u64 v[72:73], v[66:67], 0, v[142:143]
	s_mov_b64 s[98:99], 0x100000
	v_lshl_add_u64 v[192:193], v[232:233], 0, s[98:99]
	global_load_dwordx4 v[164:167], v[192:193], off
	global_load_dwordx4 v[168:171], v[192:193], off offset:64
	global_load_dwordx4 v[172:175], v[192:193], off offset:512
	global_load_dwordx4 v[176:179], v[192:193], off offset:576
	s_mov_b64 s[98:99], 0x120000
	v_lshl_add_u64 v[192:193], v[232:233], 0, s[98:99]
	global_load_dwordx4 v[180:183], v[192:193], off
	global_load_dwordx4 v[184:187], v[192:193], off offset:64
	global_load_dwordx4 v[188:191], v[192:193], off offset:512
	global_load_dwordx4 v[196:199], v[192:193], off offset:576
	s_mov_b64 s[98:99], 0x140000
	v_lshl_add_u64 v[192:193], v[232:233], 0, s[98:99]
	global_load_dwordx4 v[200:203], v[192:193], off
	global_load_dwordx4 v[204:207], v[192:193], off offset:64
	global_load_dwordx4 v[208:211], v[192:193], off offset:512
	global_load_dwordx4 v[212:215], v[192:193], off offset:576
	s_mov_b64 s[98:99], 0x160000
	v_lshl_add_u64 v[192:193], v[232:233], 0, s[98:99]
	global_load_dwordx4 v[216:219], v[192:193], off
	global_load_dwordx4 v[220:223], v[192:193], off offset:64
	global_load_dwordx4 v[224:227], v[192:193], off offset:512
	global_load_dwordx4 v[228:231], v[192:193], off offset:576
	s_waitcnt vmcnt(0)
	v_mov_b32_e32 v66, v164
	v_mov_b32_e32 v67, v165
	v_mov_b32_e32 v68, v166
	v_mov_b32_e32 v69, v167
	v_lshl_add_u64 v[74:75], s[20:21], 0, v[74:75]
	v_lshl_add_u64 v[70:71], v[70:71], 0, v[142:143]
	v_lshl_add_u64 v[74:75], v[140:141], 1, v[74:75]
	v_lshl_add_u64 v[76:77], v[74:75], 0, 32
	v_readlane_b32 s72, v234, 7
	v_readlane_b32 s73, v234, 8
	v_readlane_b32 s74, v234, 9
	v_readlane_b32 s75, v234, 10
	v_readlane_b32 s76, v234, 11
	v_readlane_b32 s77, v234, 12
	v_readlane_b32 s78, v234, 13
	v_readlane_b32 s79, v234, 14
	v_readlane_b32 s80, v234, 15
	v_readlane_b32 s81, v234, 16
	v_readlane_b32 s82, v234, 17
	v_readlane_b32 s83, v234, 18
	v_pk_add_f32 v[62:63], v[62:63], v[68:69]
	v_pk_add_f32 v[60:61], v[60:61], v[66:67]
	global_store_dwordx4 v[70:71], v[60:63], off nt
	v_cvt_pk_bf16_f32 v236, v60, v61
	v_cvt_pk_bf16_f32 v237, v62, v63
	s_nop 0
	v_mov_b32_e32 v66, v168
	v_mov_b32_e32 v67, v169
	v_mov_b32_e32 v68, v170
	v_mov_b32_e32 v69, v171
	v_mul_f32_e32 v61, v61, v61
	v_mul_f32_e32 v63, v63, v63
	v_fmac_f32_e32 v61, v60, v60
	v_fmac_f32_e32 v63, v62, v62
	v_add_f32_e32 v60, v61, v63
	v_pk_add_f32 v[58:59], v[58:59], v[68:69]
	v_pk_add_f32 v[56:57], v[56:57], v[66:67]
	global_store_dwordx4 v[70:71], v[56:59], off offset:64 nt
	v_cvt_pk_bf16_f32 v238, v56, v57
	v_cvt_pk_bf16_f32 v239, v58, v59
	s_nop 0
	s_nop 1
	v_permlane32_swap_b32_e32 v236, v238
	v_permlane32_swap_b32_e32 v237, v239
	s_nop 1
	v_permlane16_swap_b32_e32 v236, v238
	v_permlane16_swap_b32_e32 v237, v239
	v_lshl_add_u64 v[242:243], v[76:77], 0, v[240:241]
	s_nop 0
	global_store_dwordx4 v[242:243], v[236:239], off sc1
	s_nop 1
	v_mov_b32_e32 v66, v172
	v_mov_b32_e32 v67, v173
	v_mov_b32_e32 v68, v174
	v_mov_b32_e32 v69, v175
	v_lshl_add_u64 v[76:77], v[74:75], 0, s[28:29]
	v_mul_f32_e32 v57, v57, v57
	v_mul_f32_e32 v59, v59, v59
	v_fmac_f32_e32 v57, v56, v56
	v_fmac_f32_e32 v59, v58, v58
	v_add_f32_e32 v56, v57, v59
	v_add_f32_e32 v56, v60, v56
	v_pk_add_f32 v[54:55], v[54:55], v[68:69]
	v_pk_add_f32 v[52:53], v[52:53], v[66:67]
	global_store_dwordx4 v[70:71], v[52:55], off offset:512 nt
	v_cvt_pk_bf16_f32 v236, v52, v53
	v_cvt_pk_bf16_f32 v237, v54, v55
	s_nop 0
	v_mov_b32_e32 v66, v176
	v_mov_b32_e32 v67, v177
	v_mov_b32_e32 v68, v178
	v_mov_b32_e32 v69, v179
	v_mul_f32_e32 v53, v53, v53
	v_mul_f32_e32 v55, v55, v55
	v_fmac_f32_e32 v53, v52, v52
	v_fmac_f32_e32 v55, v54, v54
	v_add_f32_e32 v52, v53, v55
	v_add_f32_e32 v52, v56, v52
	v_pk_add_f32 v[50:51], v[50:51], v[68:69]
	v_pk_add_f32 v[48:49], v[48:49], v[66:67]
	v_mul_f32_e32 v54, v51, v51
	v_mul_f32_e32 v53, v49, v49
	v_fmac_f32_e32 v53, v48, v48
	v_fmac_f32_e32 v54, v50, v50
	v_add_f32_e32 v53, v53, v54
	v_add_f32_e32 v54, v52, v53
	ds_bpermute_b32 v55, v116, v54
	global_store_dwordx4 v[70:71], v[48:51], off offset:576 nt
	v_cvt_pk_bf16_f32 v238, v48, v49
	v_cvt_pk_bf16_f32 v239, v50, v51
	s_waitcnt lgkmcnt(0)
	s_nop 0
	v_add_f32_e32 v48, v54, v55
	ds_bpermute_b32 v49, v114, v48
	v_lshl_add_u64 v[50:51], v[74:75], 0, s[30:31]
	s_nop 1
	v_permlane32_swap_b32_e32 v236, v238
	v_permlane32_swap_b32_e32 v237, v239
	s_nop 1
	v_permlane16_swap_b32_e32 v236, v238
	v_permlane16_swap_b32_e32 v237, v239
	v_lshl_add_u64 v[242:243], v[50:51], 0, v[240:241]
	s_nop 0
	global_store_dwordx4 v[242:243], v[236:239], off sc1
	s_nop 1
	s_and_saveexec_b64 s[44:45], s[4:5]
	s_cbranch_execz .LBB0_309
	s_waitcnt lgkmcnt(0)
	v_add_f32_e32 v50, v48, v49
	v_lshlrev_b64 v[48:49], 7, v[64:65]
	v_lshl_add_u64 v[48:49], s[2:3], 0, v[48:49]
	v_lshl_add_u64 v[48:49], s[42:43], 2, v[48:49]
	s_lshl_b32 s10, s55, 2
	v_lshl_add_u64 v[48:49], v[48:49], 0, s[10:11]
	global_store_dword v[48:49], v50, off sc1
; __device__ __forceinline__ unsigned cvt_pk_bf16(float lo, float hi) { unsigned r; asm volatile("v_cvt_pk_bf16_f32 %0, %1, %2" : "=v"(r) : "v"(lo), "v"(hi)); return r; }
; __device__ __forceinline__ void st_wt8(void* ptr, u32x2 v) { asm volatile("global_store_dwordx2 %0, %1, off sc1" :: "v"(ptr), "v"(v) : "memory"); }
; __device__ __forceinline__ void st_wt4(void* ptr, unsigned v) { asm volatile("global_store_dword %0, %1, off sc1" :: "v"(ptr), "v"(v) : "memory"); }
;     __device__ __forceinline__ void operator()(const f32x4 (&acc)[2][2][4][2], const pg8::Unit& u, int wr, int wc, int fr, int fq) const {
;     ...
;                 const int row = row0 + ai * 128 + m * 16;
;                 float* orow = oy + (size_t)row * DM + col0;
;                 const float* xr = FIRST ? ((row < MP ? xp + (size_t)row * DM : xs + (size_t)(row - MP) * DM) + col0) : orow;
;                 float q = 0.f;
; #pragma unroll
;                 for (int bj = 0; bj < 2; ++bj)
; #pragma unroll
;                     for (int n = 0; n < 2; ++n) {
;                         const f32x4 xv = *(const f32x4*)(xr + bj * 128 + n * 16);
;                         const f32x4 o = xv + acc[ai][bj][m][n];
;                         *(f32x4*)(orow + bj * 128 + n * 16) = o;
;                         q += (o[0] * o[0] + o[1] * o[1]) + (o[2] * o[2] + o[3] * o[3]);
;                         if (FIRST) { u32x2 w; w.x = cvt_pk_bf16(o[0], o[1]); w.y = cvt_pk_bf16(o[2], o[3]); st_wt8(xb + (size_t)row * DM + col0 + bj * 128 + n * 16, w); }
;                     }
;                 q += __shfl_xor(q, 16); q += __shfl_xor(q, 32);
;                 if (fq == 0) { if (FIRST) st_wt4(ss + (size_t)row * 32 + u.pn * 4 + wc, __float_as_uint(q)); else ss[(size_t)row * 32 + u.pn * 4 + wc] = q; }
.LBB0_309:
	s_or_b64 exec, exec, s[44:45]
	v_add_u32_e32 v48, 0x90, v144
	s_waitcnt lgkmcnt(0)
	v_ashrrev_i32_e32 v49, 31, v48
	v_readlane_b32 s68, v234, 3
	v_add_u32_e32 v132, 0xffffe090, v144
	v_lshlrev_b64 v[54:55], 13, v[48:49]
	v_readlane_b32 s69, v234, 4
	v_readlane_b32 s70, v234, 5
	v_readlane_b32 s71, v234, 6
	v_lshlrev_b64 v[52:53], 13, v[132:133]
	s_movk_i32 s9, 0x1f70
	v_lshl_add_u64 v[50:51], s[68:69], 0, v[54:55]
	v_lshl_add_u64 v[52:53], s[70:71], 0, v[52:53]
	v_cmp_gt_i32_e32 vcc, s9, v144
	v_lshlrev_b64 v[58:59], 12, v[48:49]
	v_lshl_add_u64 v[54:55], s[84:85], 0, v[54:55]
	v_cndmask_b32_e32 v51, v53, v51, vcc
	v_cndmask_b32_e32 v50, v52, v50, vcc
	v_lshl_add_u64 v[56:57], v[50:51], 0, v[142:143]
	v_mov_b32_e32 v50, v180
	v_mov_b32_e32 v51, v181
	v_mov_b32_e32 v52, v182
	v_mov_b32_e32 v53, v183
	v_lshl_add_u64 v[58:59], s[20:21], 0, v[58:59]
	v_lshl_add_u64 v[54:55], v[54:55], 0, v[142:143]
	v_lshl_add_u64 v[58:59], v[140:141], 1, v[58:59]
	v_lshl_add_u64 v[60:61], v[58:59], 0, 32
	v_readlane_b32 s72, v234, 7
	v_readlane_b32 s73, v234, 8
	v_readlane_b32 s74, v234, 9
	v_readlane_b32 s75, v234, 10
	v_readlane_b32 s76, v234, 11
	v_readlane_b32 s77, v234, 12
	v_readlane_b32 s78, v234, 13
	v_readlane_b32 s79, v234, 14
	v_readlane_b32 s80, v234, 15
	v_readlane_b32 s81, v234, 16
	v_readlane_b32 s82, v234, 17
	v_readlane_b32 s83, v234, 18
	v_pk_add_f32 v[46:47], v[46:47], v[52:53]
	v_pk_add_f32 v[44:45], v[44:45], v[50:51]
	global_store_dwordx4 v[54:55], v[44:47], off nt
	v_cvt_pk_bf16_f32 v236, v44, v45
	v_cvt_pk_bf16_f32 v237, v46, v47
	s_nop 0
	v_mov_b32_e32 v50, v184
	v_mov_b32_e32 v51, v185
	v_mov_b32_e32 v52, v186
	v_mov_b32_e32 v53, v187
	v_mul_f32_e32 v45, v45, v45
	v_mul_f32_e32 v47, v47, v47
	v_fmac_f32_e32 v45, v44, v44
	v_fmac_f32_e32 v47, v46, v46
	v_add_f32_e32 v44, v45, v47
	v_pk_add_f32 v[42:43], v[42:43], v[52:53]
	v_pk_add_f32 v[40:41], v[40:41], v[50:51]
	global_store_dwordx4 v[54:55], v[40:43], off offset:64 nt
	v_cvt_pk_bf16_f32 v238, v40, v41
	v_cvt_pk_bf16_f32 v239, v42, v43
	s_nop 0
	s_nop 1
	v_permlane32_swap_b32_e32 v236, v238
	v_permlane32_swap_b32_e32 v237, v239
	s_nop 1
	v_permlane16_swap_b32_e32 v236, v238
	v_permlane16_swap_b32_e32 v237, v239
	v_lshl_add_u64 v[242:243], v[60:61], 0, v[240:241]
	s_nop 0
	global_store_dwordx4 v[242:243], v[236:239], off sc1
	s_nop 1
	v_mov_b32_e32 v50, v188
	v_mov_b32_e32 v51, v189
	v_mov_b32_e32 v52, v190
	v_mov_b32_e32 v53, v191
	v_lshl_add_u64 v[60:61], v[58:59], 0, s[28:29]
	v_mul_f32_e32 v41, v41, v41
	v_mul_f32_e32 v43, v43, v43
	v_fmac_f32_e32 v41, v40, v40
	v_fmac_f32_e32 v43, v42, v42
	v_add_f32_e32 v40, v41, v43
	v_add_f32_e32 v40, v44, v40
	v_pk_add_f32 v[38:39], v[38:39], v[52:53]
	v_pk_add_f32 v[36:37], v[36:37], v[50:51]
	global_store_dwordx4 v[54:55], v[36:39], off offset:512 nt
	v_cvt_pk_bf16_f32 v236, v36, v37
	v_cvt_pk_bf16_f32 v237, v38, v39
	s_nop 0
	v_mov_b32_e32 v50, v196
	v_mov_b32_e32 v51, v197
	v_mov_b32_e32 v52, v198
	v_mov_b32_e32 v53, v199
	v_mul_f32_e32 v37, v37, v37
	v_mul_f32_e32 v39, v39, v39
	v_fmac_f32_e32 v37, v36, v36
	v_fmac_f32_e32 v39, v38, v38
	v_add_f32_e32 v36, v37, v39
	v_add_f32_e32 v36, v40, v36
	v_pk_add_f32 v[34:35], v[34:35], v[52:53]
	v_pk_add_f32 v[32:33], v[32:33], v[50:51]
	v_mul_f32_e32 v38, v35, v35
	v_mul_f32_e32 v37, v33, v33
	v_fmac_f32_e32 v37, v32, v32
	v_fmac_f32_e32 v38, v34, v34
	v_add_f32_e32 v37, v37, v38
	v_add_f32_e32 v38, v36, v37
	ds_bpermute_b32 v39, v116, v38
	global_store_dwordx4 v[54:55], v[32:35], off offset:576 nt
	v_cvt_pk_bf16_f32 v238, v32, v33
	v_cvt_pk_bf16_f32 v239, v34, v35
	s_waitcnt lgkmcnt(0)
	s_nop 0
	v_add_f32_e32 v32, v38, v39
	ds_bpermute_b32 v33, v114, v32
	v_lshl_add_u64 v[34:35], v[58:59], 0, s[30:31]
	s_nop 1
	v_permlane32_swap_b32_e32 v236, v238
	v_permlane32_swap_b32_e32 v237, v239
	s_nop 1
	v_permlane16_swap_b32_e32 v236, v238
	v_permlane16_swap_b32_e32 v237, v239
	v_lshl_add_u64 v[242:243], v[34:35], 0, v[240:241]
	s_nop 0
	global_store_dwordx4 v[242:243], v[236:239], off sc1
	s_nop 1
	s_and_saveexec_b64 s[44:45], s[4:5]
	s_cbranch_execz .LBB0_311
	s_waitcnt lgkmcnt(0)
	v_add_f32_e32 v34, v32, v33
	v_lshlrev_b64 v[32:33], 7, v[48:49]
	v_lshl_add_u64 v[32:33], s[2:3], 0, v[32:33]
	v_lshl_add_u64 v[32:33], s[42:43], 2, v[32:33]
	s_lshl_b32 s10, s55, 2
	v_lshl_add_u64 v[32:33], v[32:33], 0, s[10:11]
	global_store_dword v[32:33], v34, off sc1
; __device__ __forceinline__ unsigned cvt_pk_bf16(float lo, float hi) { unsigned r; asm volatile("v_cvt_pk_bf16_f32 %0, %1, %2" : "=v"(r) : "v"(lo), "v"(hi)); return r; }
; __device__ __forceinline__ void st_wt8(void* ptr, u32x2 v) { asm volatile("global_store_dwordx2 %0, %1, off sc1" :: "v"(ptr), "v"(v) : "memory"); }
; __device__ __forceinline__ void st_wt4(void* ptr, unsigned v) { asm volatile("global_store_dword %0, %1, off sc1" :: "v"(ptr), "v"(v) : "memory"); }
;     __device__ __forceinline__ void operator()(const f32x4 (&acc)[2][2][4][2], const pg8::Unit& u, int wr, int wc, int fr, int fq) const {
;     ...
;                 const int row = row0 + ai * 128 + m * 16;
;                 float* orow = oy + (size_t)row * DM + col0;
;                 const float* xr = FIRST ? ((row < MP ? xp + (size_t)row * DM : xs + (size_t)(row - MP) * DM) + col0) : orow;
;                 float q = 0.f;
; #pragma unroll
;                 for (int bj = 0; bj < 2; ++bj)
; #pragma unroll
;                     for (int n = 0; n < 2; ++n) {
;                         const f32x4 xv = *(const f32x4*)(xr + bj * 128 + n * 16);
;                         const f32x4 o = xv + acc[ai][bj][m][n];
;                         *(f32x4*)(orow + bj * 128 + n * 16) = o;
;                         q += (o[0] * o[0] + o[1] * o[1]) + (o[2] * o[2] + o[3] * o[3]);
;                         if (FIRST) { u32x2 w; w.x = cvt_pk_bf16(o[0], o[1]); w.y = cvt_pk_bf16(o[2], o[3]); st_wt8(xb + (size_t)row * DM + col0 + bj * 128 + n * 16, w); }
;                     }
;                 q += __shfl_xor(q, 16); q += __shfl_xor(q, 32);
;                 if (fq == 0) { if (FIRST) st_wt4(ss + (size_t)row * 32 + u.pn * 4 + wc, __float_as_uint(q)); else ss[(size_t)row * 32 + u.pn * 4 + wc] = q; }
.LBB0_311:
	s_or_b64 exec, exec, s[44:45]
	v_add_u32_e32 v32, 0xa0, v144
	s_waitcnt lgkmcnt(0)
	v_ashrrev_i32_e32 v33, 31, v32
	v_readlane_b32 s68, v234, 3
	v_add_u32_e32 v132, 0xffffe0a0, v144
	v_lshlrev_b64 v[38:39], 13, v[32:33]
	v_readlane_b32 s69, v234, 4
	v_readlane_b32 s70, v234, 5
	v_readlane_b32 s71, v234, 6
	v_lshlrev_b64 v[36:37], 13, v[132:133]
	s_movk_i32 s9, 0x1f60
	v_lshl_add_u64 v[34:35], s[68:69], 0, v[38:39]
	v_lshl_add_u64 v[36:37], s[70:71], 0, v[36:37]
	v_cmp_gt_i32_e32 vcc, s9, v144
	v_lshlrev_b64 v[42:43], 12, v[32:33]
	v_lshl_add_u64 v[38:39], s[84:85], 0, v[38:39]
	v_cndmask_b32_e32 v35, v37, v35, vcc
	v_cndmask_b32_e32 v34, v36, v34, vcc
	v_lshl_add_u64 v[40:41], v[34:35], 0, v[142:143]
	v_mov_b32_e32 v34, v200
	v_mov_b32_e32 v35, v201
	v_mov_b32_e32 v36, v202
	v_mov_b32_e32 v37, v203
	v_lshl_add_u64 v[42:43], s[20:21], 0, v[42:43]
	v_lshl_add_u64 v[38:39], v[38:39], 0, v[142:143]
	v_lshl_add_u64 v[42:43], v[140:141], 1, v[42:43]
	v_lshl_add_u64 v[44:45], v[42:43], 0, 32
	v_readlane_b32 s72, v234, 7
	v_readlane_b32 s73, v234, 8
	v_readlane_b32 s74, v234, 9
	v_readlane_b32 s75, v234, 10
	v_readlane_b32 s76, v234, 11
	v_readlane_b32 s77, v234, 12
	v_readlane_b32 s78, v234, 13
	v_readlane_b32 s79, v234, 14
	v_readlane_b32 s80, v234, 15
	v_readlane_b32 s81, v234, 16
	v_readlane_b32 s82, v234, 17
	v_readlane_b32 s83, v234, 18
	v_pk_add_f32 v[30:31], v[30:31], v[36:37]
	v_pk_add_f32 v[28:29], v[28:29], v[34:35]
	global_store_dwordx4 v[38:39], v[28:31], off nt
	v_cvt_pk_bf16_f32 v236, v28, v29
	v_cvt_pk_bf16_f32 v237, v30, v31
	s_nop 0
	v_mov_b32_e32 v34, v204
	v_mov_b32_e32 v35, v205
	v_mov_b32_e32 v36, v206
	v_mov_b32_e32 v37, v207
	v_mul_f32_e32 v29, v29, v29
	v_mul_f32_e32 v31, v31, v31
	v_fmac_f32_e32 v29, v28, v28
	v_fmac_f32_e32 v31, v30, v30
	v_add_f32_e32 v28, v29, v31
	v_pk_add_f32 v[26:27], v[26:27], v[36:37]
	v_pk_add_f32 v[24:25], v[24:25], v[34:35]
	global_store_dwordx4 v[38:39], v[24:27], off offset:64 nt
	v_cvt_pk_bf16_f32 v238, v24, v25
	v_cvt_pk_bf16_f32 v239, v26, v27
	s_nop 0
	s_nop 1
	v_permlane32_swap_b32_e32 v236, v238
	v_permlane32_swap_b32_e32 v237, v239
	s_nop 1
	v_permlane16_swap_b32_e32 v236, v238
	v_permlane16_swap_b32_e32 v237, v239
	v_lshl_add_u64 v[242:243], v[44:45], 0, v[240:241]
	s_nop 0
	global_store_dwordx4 v[242:243], v[236:239], off sc1
	s_nop 1
	v_mov_b32_e32 v34, v208
	v_mov_b32_e32 v35, v209
	v_mov_b32_e32 v36, v210
	v_mov_b32_e32 v37, v211
	v_lshl_add_u64 v[44:45], v[42:43], 0, s[28:29]
	v_mul_f32_e32 v25, v25, v25
	v_mul_f32_e32 v27, v27, v27
	v_fmac_f32_e32 v25, v24, v24
	v_fmac_f32_e32 v27, v26, v26
	v_add_f32_e32 v24, v25, v27
	v_add_f32_e32 v24, v28, v24
	v_pk_add_f32 v[22:23], v[22:23], v[36:37]
	v_pk_add_f32 v[20:21], v[20:21], v[34:35]
	global_store_dwordx4 v[38:39], v[20:23], off offset:512 nt
	v_cvt_pk_bf16_f32 v236, v20, v21
	v_cvt_pk_bf16_f32 v237, v22, v23
	s_nop 0
	v_mov_b32_e32 v34, v212
	v_mov_b32_e32 v35, v213
	v_mov_b32_e32 v36, v214
	v_mov_b32_e32 v37, v215
	v_mul_f32_e32 v21, v21, v21
	v_mul_f32_e32 v23, v23, v23
	v_fmac_f32_e32 v21, v20, v20
	v_fmac_f32_e32 v23, v22, v22
	v_add_f32_e32 v20, v21, v23
	v_add_f32_e32 v20, v24, v20
	v_pk_add_f32 v[18:19], v[18:19], v[36:37]
	v_pk_add_f32 v[16:17], v[16:17], v[34:35]
	v_mul_f32_e32 v22, v19, v19
	v_mul_f32_e32 v21, v17, v17
	v_fmac_f32_e32 v21, v16, v16
	v_fmac_f32_e32 v22, v18, v18
	v_add_f32_e32 v21, v21, v22
	v_add_f32_e32 v22, v20, v21
	ds_bpermute_b32 v23, v116, v22
	global_store_dwordx4 v[38:39], v[16:19], off offset:576 nt
	v_cvt_pk_bf16_f32 v238, v16, v17
	v_cvt_pk_bf16_f32 v239, v18, v19
	s_waitcnt lgkmcnt(0)
	s_nop 0
	v_add_f32_e32 v16, v22, v23
	ds_bpermute_b32 v17, v114, v16
	v_lshl_add_u64 v[18:19], v[42:43], 0, s[30:31]
	s_nop 1
	v_permlane32_swap_b32_e32 v236, v238
	v_permlane32_swap_b32_e32 v237, v239
	s_nop 1
	v_permlane16_swap_b32_e32 v236, v238
	v_permlane16_swap_b32_e32 v237, v239
	v_lshl_add_u64 v[242:243], v[18:19], 0, v[240:241]
	s_nop 0
	global_store_dwordx4 v[242:243], v[236:239], off sc1
	s_nop 1
	s_and_saveexec_b64 s[44:45], s[4:5]
	s_cbranch_execz .LBB0_313
	s_waitcnt lgkmcnt(0)
	v_add_f32_e32 v18, v16, v17
	v_lshlrev_b64 v[16:17], 7, v[32:33]
	v_lshl_add_u64 v[16:17], s[2:3], 0, v[16:17]
	v_lshl_add_u64 v[16:17], s[42:43], 2, v[16:17]
	s_lshl_b32 s10, s55, 2
	v_lshl_add_u64 v[16:17], v[16:17], 0, s[10:11]
	global_store_dword v[16:17], v18, off sc1
; __device__ __forceinline__ unsigned cvt_pk_bf16(float lo, float hi) { unsigned r; asm volatile("v_cvt_pk_bf16_f32 %0, %1, %2" : "=v"(r) : "v"(lo), "v"(hi)); return r; }
; __device__ __forceinline__ void st_wt8(void* ptr, u32x2 v) { asm volatile("global_store_dwordx2 %0, %1, off sc1" :: "v"(ptr), "v"(v) : "memory"); }
; __device__ __forceinline__ void st_wt4(void* ptr, unsigned v) { asm volatile("global_store_dword %0, %1, off sc1" :: "v"(ptr), "v"(v) : "memory"); }
;     __device__ __forceinline__ void operator()(const f32x4 (&acc)[2][2][4][2], const pg8::Unit& u, int wr, int wc, int fr, int fq) const {
;     ...
;                 const int row = row0 + ai * 128 + m * 16;
;                 float* orow = oy + (size_t)row * DM + col0;
;                 const float* xr = FIRST ? ((row < MP ? xp + (size_t)row * DM : xs + (size_t)(row - MP) * DM) + col0) : orow;
;                 float q = 0.f;
; #pragma unroll
;                 for (int bj = 0; bj < 2; ++bj)
; #pragma unroll
;                     for (int n = 0; n < 2; ++n) {
;                         const f32x4 xv = *(const f32x4*)(xr + bj * 128 + n * 16);
;                         const f32x4 o = xv + acc[ai][bj][m][n];
;                         *(f32x4*)(orow + bj * 128 + n * 16) = o;
;                         q += (o[0] * o[0] + o[1] * o[1]) + (o[2] * o[2] + o[3] * o[3]);
;                         if (FIRST) { u32x2 w; w.x = cvt_pk_bf16(o[0], o[1]); w.y = cvt_pk_bf16(o[2], o[3]); st_wt8(xb + (size_t)row * DM + col0 + bj * 128 + n * 16, w); }
;                     }
;                 q += __shfl_xor(q, 16); q += __shfl_xor(q, 32);
;                 if (fq == 0) { if (FIRST) st_wt4(ss + (size_t)row * 32 + u.pn * 4 + wc, __float_as_uint(q)); else ss[(size_t)row * 32 + u.pn * 4 + wc] = q; }
.LBB0_313:
	s_or_b64 exec, exec, s[44:45]
	v_add_u32_e32 v16, 0xb0, v144
	s_waitcnt lgkmcnt(0)
	v_ashrrev_i32_e32 v17, 31, v16
	v_readlane_b32 s68, v234, 3
	v_add_u32_e32 v132, 0xffffe0b0, v144
	v_lshlrev_b64 v[22:23], 13, v[16:17]
	v_readlane_b32 s69, v234, 4
	v_readlane_b32 s70, v234, 5
	v_readlane_b32 s71, v234, 6
	v_lshlrev_b64 v[20:21], 13, v[132:133]
	s_movk_i32 s9, 0x1f50
	v_lshl_add_u64 v[18:19], s[68:69], 0, v[22:23]
	v_lshl_add_u64 v[20:21], s[70:71], 0, v[20:21]
	v_cmp_gt_i32_e32 vcc, s9, v144
	v_lshlrev_b64 v[26:27], 12, v[16:17]
	v_lshl_add_u64 v[22:23], s[84:85], 0, v[22:23]
	v_cndmask_b32_e32 v19, v21, v19, vcc
	v_cndmask_b32_e32 v18, v20, v18, vcc
	v_lshl_add_u64 v[24:25], v[18:19], 0, v[142:143]
	v_mov_b32_e32 v18, v216
	v_mov_b32_e32 v19, v217
	v_mov_b32_e32 v20, v218
	v_mov_b32_e32 v21, v219
	v_lshl_add_u64 v[26:27], s[20:21], 0, v[26:27]
	v_lshl_add_u64 v[22:23], v[22:23], 0, v[142:143]
	v_lshl_add_u64 v[26:27], v[140:141], 1, v[26:27]
	v_lshl_add_u64 v[28:29], v[26:27], 0, 32
	v_readlane_b32 s72, v234, 7
	v_readlane_b32 s73, v234, 8
	v_readlane_b32 s74, v234, 9
	v_readlane_b32 s75, v234, 10
	v_readlane_b32 s76, v234, 11
	v_readlane_b32 s77, v234, 12
	v_readlane_b32 s78, v234, 13
	v_readlane_b32 s79, v234, 14
	v_readlane_b32 s80, v234, 15
	v_readlane_b32 s81, v234, 16
	v_readlane_b32 s82, v234, 17
	v_readlane_b32 s83, v234, 18
	v_pk_add_f32 v[14:15], v[14:15], v[20:21]
	v_pk_add_f32 v[12:13], v[12:13], v[18:19]
	global_store_dwordx4 v[22:23], v[12:15], off nt
	v_cvt_pk_bf16_f32 v236, v12, v13
	v_cvt_pk_bf16_f32 v237, v14, v15
	s_nop 0
	v_mov_b32_e32 v18, v220
	v_mov_b32_e32 v19, v221
	v_mov_b32_e32 v20, v222
	v_mov_b32_e32 v21, v223
	v_mul_f32_e32 v13, v13, v13
	v_mul_f32_e32 v15, v15, v15
	v_fmac_f32_e32 v13, v12, v12
	v_fmac_f32_e32 v15, v14, v14
	v_add_f32_e32 v12, v13, v15
	v_pk_add_f32 v[10:11], v[10:11], v[20:21]
	v_pk_add_f32 v[8:9], v[8:9], v[18:19]
	global_store_dwordx4 v[22:23], v[8:11], off offset:64 nt
	v_cvt_pk_bf16_f32 v238, v8, v9
	v_cvt_pk_bf16_f32 v239, v10, v11
	s_nop 0
	s_nop 1
	v_permlane32_swap_b32_e32 v236, v238
	v_permlane32_swap_b32_e32 v237, v239
	s_nop 1
	v_permlane16_swap_b32_e32 v236, v238
	v_permlane16_swap_b32_e32 v237, v239
	v_lshl_add_u64 v[242:243], v[28:29], 0, v[240:241]
	s_nop 0
	global_store_dwordx4 v[242:243], v[236:239], off sc1
	s_nop 1
	v_mov_b32_e32 v18, v224
	v_mov_b32_e32 v19, v225
	v_mov_b32_e32 v20, v226
	v_mov_b32_e32 v21, v227
	v_lshl_add_u64 v[28:29], v[26:27], 0, s[28:29]
	v_mul_f32_e32 v9, v9, v9
	v_mul_f32_e32 v11, v11, v11
	v_fmac_f32_e32 v9, v8, v8
	v_fmac_f32_e32 v11, v10, v10
	v_add_f32_e32 v8, v9, v11
	v_add_f32_e32 v8, v12, v8
	v_pk_add_f32 v[6:7], v[6:7], v[20:21]
	v_pk_add_f32 v[4:5], v[4:5], v[18:19]
	global_store_dwordx4 v[22:23], v[4:7], off offset:512 nt
	v_cvt_pk_bf16_f32 v236, v4, v5
	v_cvt_pk_bf16_f32 v237, v6, v7
	s_nop 0
	v_mov_b32_e32 v18, v228
	v_mov_b32_e32 v19, v229
	v_mov_b32_e32 v20, v230
	v_mov_b32_e32 v21, v231
	v_mul_f32_e32 v5, v5, v5
	v_mul_f32_e32 v7, v7, v7
	v_fmac_f32_e32 v5, v4, v4
	v_fmac_f32_e32 v7, v6, v6
	v_add_f32_e32 v4, v5, v7
	v_add_f32_e32 v4, v8, v4
	v_pk_add_f32 v[2:3], v[2:3], v[20:21]
	v_pk_add_f32 v[0:1], v[0:1], v[18:19]
	v_mul_f32_e32 v6, v3, v3
	v_mul_f32_e32 v5, v1, v1
	v_fmac_f32_e32 v5, v0, v0
	v_fmac_f32_e32 v6, v2, v2
	v_add_f32_e32 v5, v5, v6
	v_add_f32_e32 v6, v4, v5
	ds_bpermute_b32 v7, v116, v6
	global_store_dwordx4 v[22:23], v[0:3], off offset:576 nt
	v_cvt_pk_bf16_f32 v238, v0, v1
	v_cvt_pk_bf16_f32 v239, v2, v3
	s_waitcnt lgkmcnt(0)
	s_nop 0
	v_add_f32_e32 v0, v6, v7
	ds_bpermute_b32 v1, v114, v0
	v_lshl_add_u64 v[2:3], v[26:27], 0, s[30:31]
	s_nop 1
	v_permlane32_swap_b32_e32 v236, v238
	v_permlane32_swap_b32_e32 v237, v239
	s_nop 1
	v_permlane16_swap_b32_e32 v236, v238
	v_permlane16_swap_b32_e32 v237, v239
	v_lshl_add_u64 v[242:243], v[2:3], 0, v[240:241]
	s_nop 0
	global_store_dwordx4 v[242:243], v[236:239], off sc1
	s_nop 1
	s_and_saveexec_b64 s[44:45], s[4:5]
	s_cbranch_execnz .LBB0_316
	s_or_b64 exec, exec, s[44:45]
	s_andn2_b64 vcc, exec, s[36:37]
	s_mov_b64 s[36:37], -1
	s_cbranch_vccz .LBB0_317
